# hg_sequence: log chains write results in place (16 v_mov removed), stage-O output stores use saddr form with shared 32-bit lane offsets (30 fewer VALU per chunk)
# speedup vs baseline: 1.0015x; 1.0015x over previous
.LBB0_1409:
	v_add_u32_e32 v0, s82, v67
	v_bfe_u32 v62, v58, 16, 1
	s_movk_i32 s26, 0x7fff
	v_add3_u32 v58, v58, v62, s26
	v_mad_u64_u32 v[62:63], s[2:3], v0, s73, v[66:67]
	v_bfe_u32 v0, v59, 16, 1
	v_add3_u32 v0, v59, v0, s26
	ds_write_b16_d16_hi v62, v0 offset:144
	v_bfe_u32 v0, v60, 16, 1
	v_add3_u32 v0, v60, v0, s26
	ds_write_b16_d16_hi v62, v0 offset:288
	v_bfe_u32 v0, v61, 16, 1
	v_add3_u32 v0, v61, v0, s26
	ds_write_b16_d16_hi v62, v0 offset:432
	v_add_u32_e32 v0, s56, v99
	v_mul_lo_u32 v0, v0, s73
	s_add_i32 s2, 0, 0x15200
	v_lshlrev_b32_e32 v94, 4, v100
	v_add3_u32 v0, s2, v0, v94
	s_add_i32 s2, 0, 0x1e200
	v_add_u32_e32 v95, s2, v94
	s_movk_i32 s2, 0x110
	v_lshlrev_b32_e32 v86, 3, v100
	v_mul_lo_u32 v87, v99, s2
	v_add3_u32 v97, 0, v86, v87
	ds_write_b16_d16_hi v62, v58
	v_add_u32_e32 v96, 0x6000, v97
	v_pk_add_f32 v[84:85], v[84:85], v[64:65]
	s_waitcnt lgkmcnt(0)
	s_barrier
	v_cvt_pk_bf16_f32 v78, v50, v51
	v_cvt_pk_bf16_f32 v79, v52, v53
	v_cvt_pk_bf16_f32 v80, v54, v55
	v_cvt_pk_bf16_f32 v81, v56, v57
	v_cvt_pk_bf16_f32 v74, v42, v43
	v_cvt_pk_bf16_f32 v75, v44, v45
	v_cvt_pk_bf16_f32 v76, v46, v47
	v_cvt_pk_bf16_f32 v77, v48, v49
	v_cvt_pk_bf16_f32 v70, v30, v31
	v_cvt_pk_bf16_f32 v71, v32, v33
	v_cvt_pk_bf16_f32 v72, v38, v39
	v_cvt_pk_bf16_f32 v73, v40, v41
	v_cvt_pk_bf16_f32 v66, v26, v27
	v_cvt_pk_bf16_f32 v67, v28, v29
	v_cvt_pk_bf16_f32 v68, v34, v35
	v_cvt_pk_bf16_f32 v69, v36, v37
	ds_read_b128 v[62:65], v0
	ds_read_b128 v[58:61], v0 offset:64
	ds_read2_b64 v[128:131], v96 offset0:128 offset1:132
	ds_read2_b64 v[132:135], v96 offset0:136 offset1:140
	ds_read2_b64 v[136:139], v96 offset0:144 offset1:148
	ds_read2_b64 v[140:143], v96 offset0:152 offset1:156
	v_lshl_add_u32 v0, v100, 12, v99
	v_mul_lo_u32 v96, v99, s73
	v_add_u32_e32 v108, 0x7000, v97
	v_add_u32_e32 v127, v95, v96
	ds_read_b128 v[144:147], v127
	ds_read_b128 v[148:151], v127 offset:64
	ds_read2_b64 v[152:155], v108 offset0:160 offset1:164
	ds_read2_b64 v[156:159], v108 offset0:168 offset1:172
	ds_read2_b64 v[160:163], v108 offset0:176 offset1:180
	ds_read2_b64 v[164:167], v108 offset0:184 offset1:188
	ds_read_b128 v[168:171], v127 offset:2304
	ds_read_b128 v[172:175], v127 offset:2368
	s_waitcnt lgkmcnt(11)
	v_mfma_f32_16x16x32_bf16 v[86:89], v[128:131], v[78:81], 0
	s_waitcnt lgkmcnt(10)
	v_mfma_f32_16x16x32_bf16 v[86:89], v[132:135], v[74:77], v[86:89]
	s_waitcnt lgkmcnt(9)
	v_mfma_f32_16x16x32_bf16 v[86:89], v[136:139], v[70:73], v[86:89]
	s_waitcnt lgkmcnt(8)
	v_mfma_f32_16x16x32_bf16 v[86:89], v[140:143], v[66:69], v[86:89]
	s_waitcnt lgkmcnt(7)
	v_mfma_f32_16x16x32_bf16 v[86:89], v[144:147], v[62:65], v[86:89]
	s_waitcnt lgkmcnt(6)
	v_mfma_f32_16x16x32_bf16 v[100:103], v[148:151], v[58:61], v[86:89]
	v_add_u32_e32 v99, 0x8000, v97
	ds_read2_b64 v[128:131], v99 offset0:192 offset1:196
	ds_read2_b64 v[132:135], v99 offset0:200 offset1:204
	ds_read2_b64 v[136:139], v99 offset0:208 offset1:212
	ds_read2_b64 v[140:143], v99 offset0:216 offset1:220
	ds_read_b128 v[144:147], v127 offset:4608
	ds_read_b128 v[148:151], v127 offset:4672
	v_lshlrev_b32_e32 v86, 2, v0
	s_add_u32 s2, s74, 0xfffd0000
	s_addc_u32 s3, s75, -1
	v_add_u32_e32 v86, 0x1000, v86
	v_add_u32_e32 v87, 0x2000, v86
	global_store_dword v86, v100, s[2:3] offset:-4096
	global_store_dword v86, v101, s[2:3]
	global_store_dword v87, v102, s[2:3] offset:-4096
	global_store_dword v87, v103, s[2:3]
	s_waitcnt lgkmcnt(11)
	v_mfma_f32_16x16x32_bf16 v[100:103], v[152:155], v[78:81], 0
	s_waitcnt lgkmcnt(10)
	v_mfma_f32_16x16x32_bf16 v[100:103], v[156:159], v[74:77], v[100:103]
	s_waitcnt lgkmcnt(9)
	v_mfma_f32_16x16x32_bf16 v[100:103], v[160:163], v[70:73], v[100:103]
	s_waitcnt lgkmcnt(8)
	v_mfma_f32_16x16x32_bf16 v[100:103], v[164:167], v[66:69], v[100:103]
	s_waitcnt lgkmcnt(7)
	v_mfma_f32_16x16x32_bf16 v[100:103], v[168:171], v[62:65], v[100:103]
	s_waitcnt lgkmcnt(6)
	v_mfma_f32_16x16x32_bf16 v[100:103], v[172:175], v[58:61], v[100:103]
	v_add_u32_e32 v97, 0x9000, v97
	ds_read2_b64 v[152:155], v97 offset0:224 offset1:228
	ds_read2_b64 v[156:159], v97 offset0:232 offset1:236
	ds_read2_b64 v[160:163], v97 offset0:240 offset1:244
	ds_read2_b64 v[164:167], v97 offset0:248 offset1:252
	ds_read_b128 v[168:171], v127 offset:6912
	ds_read_b128 v[172:175], v127 offset:6976
	s_add_u32 s2, s74, 0xfffe0000
	s_addc_u32 s3, s75, -1
	global_store_dword v86, v100, s[2:3] offset:-4096
	global_store_dword v86, v101, s[2:3]
	global_store_dword v87, v102, s[2:3] offset:-4096
	global_store_dword v87, v103, s[2:3]
	s_waitcnt lgkmcnt(11)
	v_mfma_f32_16x16x32_bf16 v[100:103], v[128:131], v[78:81], 0
	s_waitcnt lgkmcnt(10)
	v_mfma_f32_16x16x32_bf16 v[100:103], v[132:135], v[74:77], v[100:103]
	s_waitcnt lgkmcnt(9)
	v_mfma_f32_16x16x32_bf16 v[100:103], v[136:139], v[70:73], v[100:103]
	s_waitcnt lgkmcnt(8)
	v_mfma_f32_16x16x32_bf16 v[100:103], v[140:143], v[66:69], v[100:103]
	s_waitcnt lgkmcnt(7)
	v_mfma_f32_16x16x32_bf16 v[100:103], v[144:147], v[62:65], v[100:103]
	s_waitcnt lgkmcnt(6)
	v_mfma_f32_16x16x32_bf16 v[100:103], v[148:151], v[58:61], v[100:103]
	v_add_u32_e32 v127, 0x19a00, v94
	v_add_u32_e32 v127, v127, v96
	ds_read_b128 v[128:131], v94 offset:6144
	ds_read_b128 v[132:135], v127
	ds_read_b128 v[136:139], v127 offset:64
	ds_read_b128 v[140:143], v94 offset:6208
	ds_read_b128 v[144:147], v127 offset:2304
	ds_read_b128 v[148:151], v127 offset:2368
	s_add_u32 s2, s74, 0xffff0000
	s_addc_u32 s3, s75, -1
	global_store_dword v86, v100, s[2:3] offset:-4096
	global_store_dword v86, v101, s[2:3]
	global_store_dword v87, v102, s[2:3] offset:-4096
	global_store_dword v87, v103, s[2:3]
	s_waitcnt lgkmcnt(11)
	v_mfma_f32_16x16x32_bf16 v[78:81], v[152:155], v[78:81], 0
	s_waitcnt lgkmcnt(10)
	v_mfma_f32_16x16x32_bf16 v[74:77], v[156:159], v[74:77], v[78:81]
	s_waitcnt lgkmcnt(9)
	v_mfma_f32_16x16x32_bf16 v[70:73], v[160:163], v[70:73], v[74:77]
	s_waitcnt lgkmcnt(8)
	v_mfma_f32_16x16x32_bf16 v[66:69], v[164:167], v[66:69], v[70:73]
	s_waitcnt lgkmcnt(7)
	v_mfma_f32_16x16x32_bf16 v[66:69], v[168:171], v[62:65], v[66:69]
	s_waitcnt lgkmcnt(6)
	v_mfma_f32_16x16x32_bf16 v[66:69], v[172:175], v[58:61], v[66:69]
	ds_read_b128 v[152:155], v94 offset:6272
	ds_read_b128 v[156:159], v127 offset:4608
	ds_read_b128 v[160:163], v127 offset:4672
	ds_read_b128 v[164:167], v94 offset:6336
	ds_read_b128 v[168:171], v127 offset:6912
	ds_read_b128 v[172:175], v127 offset:6976
	s_nop 1
	global_store_dword v86, v66, s[74:75] offset:-4096
	global_store_dword v86, v67, s[74:75]
	global_store_dword v87, v68, s[74:75] offset:-4096
	global_store_dword v87, v69, s[74:75]
	s_add_u32 s34, s34, 0x20000
	s_addc_u32 s35, s35, 0
	s_add_u32 s74, s74, 0x40000
	s_addc_u32 s75, s75, 0
	s_mov_b32 s2, 0x19a00
	s_cmp_eq_u32 s34, 0x400000
	s_waitcnt lgkmcnt(11)
	v_pk_mul_f32 v[50:51], v[50:51], v[128:129]
	v_pk_mul_f32 v[52:53], v[52:53], v[130:131]
	s_waitcnt lgkmcnt(10)
	s_nop 0
	v_mfma_f32_16x16x32_bf16 v[50:53], v[132:135], v[62:65], v[50:53]
	s_waitcnt lgkmcnt(9)
	v_mfma_f32_16x16x32_bf16 v[50:53], v[136:139], v[58:61], v[50:53]
	ds_read_b128 v[128:131], v94 offset:6400
	ds_read_b128 v[132:135], v127 offset:9216
	ds_read_b128 v[136:139], v127 offset:9280
	s_waitcnt lgkmcnt(11)
	v_pk_mul_f32 v[54:55], v[54:55], v[140:141]
	v_pk_mul_f32 v[56:57], v[56:57], v[142:143]
	s_waitcnt lgkmcnt(10)
	s_nop 0
	v_mfma_f32_16x16x32_bf16 v[54:57], v[144:147], v[62:65], v[54:57]
	s_waitcnt lgkmcnt(9)
	v_mfma_f32_16x16x32_bf16 v[54:57], v[148:151], v[58:61], v[54:57]
	ds_read_b128 v[140:143], v94 offset:6464
	ds_read_b128 v[144:147], v127 offset:11520
	ds_read_b128 v[148:151], v127 offset:11584
	s_waitcnt lgkmcnt(11)
	v_pk_mul_f32 v[42:43], v[42:43], v[152:153]
	v_pk_mul_f32 v[44:45], v[44:45], v[154:155]
	s_waitcnt lgkmcnt(10)
	s_nop 0
	v_mfma_f32_16x16x32_bf16 v[42:45], v[156:159], v[62:65], v[42:45]
	s_waitcnt lgkmcnt(9)
	v_mfma_f32_16x16x32_bf16 v[42:45], v[160:163], v[58:61], v[42:45]
	ds_read_b128 v[152:155], v94 offset:6528
	ds_read_b128 v[156:159], v127 offset:13824
	ds_read_b128 v[160:163], v127 offset:13888
	s_waitcnt lgkmcnt(11)
	v_pk_mul_f32 v[46:47], v[46:47], v[164:165]
	v_pk_mul_f32 v[48:49], v[48:49], v[166:167]
	s_waitcnt lgkmcnt(10)
	s_nop 0
	v_mfma_f32_16x16x32_bf16 v[46:49], v[168:171], v[62:65], v[46:49]
	s_waitcnt lgkmcnt(9)
	v_mfma_f32_16x16x32_bf16 v[46:49], v[172:175], v[58:61], v[46:49]
	ds_read_b128 v[164:167], v94 offset:6592
	ds_read_b128 v[168:171], v127 offset:16128
	ds_read_b128 v[172:175], v127 offset:16192
	s_waitcnt lgkmcnt(11)
	v_pk_mul_f32 v[30:31], v[30:31], v[128:129]
	v_pk_mul_f32 v[32:33], v[32:33], v[130:131]
	s_waitcnt lgkmcnt(10)
	s_nop 0
	v_mfma_f32_16x16x32_bf16 v[30:33], v[132:135], v[62:65], v[30:33]
	s_waitcnt lgkmcnt(9)
	v_mfma_f32_16x16x32_bf16 v[30:33], v[136:139], v[58:61], v[30:33]
	s_waitcnt lgkmcnt(8)
	v_pk_mul_f32 v[38:39], v[38:39], v[140:141]
	v_pk_mul_f32 v[40:41], v[40:41], v[142:143]
	s_waitcnt lgkmcnt(7)
	s_nop 0
	v_mfma_f32_16x16x32_bf16 v[38:41], v[144:147], v[62:65], v[38:41]
	s_waitcnt lgkmcnt(6)
	v_mfma_f32_16x16x32_bf16 v[38:41], v[148:151], v[58:61], v[38:41]
	s_waitcnt lgkmcnt(5)
	v_pk_mul_f32 v[26:27], v[26:27], v[152:153]
	v_pk_mul_f32 v[28:29], v[28:29], v[154:155]
	s_waitcnt lgkmcnt(4)
	s_nop 0
	v_mfma_f32_16x16x32_bf16 v[26:29], v[156:159], v[62:65], v[26:29]
	s_waitcnt lgkmcnt(3)
	v_mfma_f32_16x16x32_bf16 v[26:29], v[160:163], v[58:61], v[26:29]
	s_waitcnt lgkmcnt(2)
	v_pk_mul_f32 v[34:35], v[34:35], v[164:165]
	v_pk_mul_f32 v[36:37], v[36:37], v[166:167]
	s_waitcnt lgkmcnt(1)
	s_nop 0
	v_mfma_f32_16x16x32_bf16 v[34:37], v[168:171], v[62:65], v[34:37]
	s_waitcnt lgkmcnt(0)
	s_barrier
	v_mfma_f32_16x16x32_bf16 v[34:37], v[172:175], v[58:61], v[34:37]
	s_cbranch_scc1 .LBB0_1472
.LBB0_1410:
	s_waitcnt vmcnt(38)
	v_lshlrev_b32_e32 v101, 16, v16
	v_sub_f32_e32 v128, 1.0, v101
	v_max_f32_e32 v128, 0x3a800000, v128
	s_mov_b32 s2, 0x800000
	s_mov_b32 s3, 0x3f317217
	s_mov_b32 s28, 0x7f800000
	v_log_f32_e32 v128, v128
	v_and_b32_e32 v104, 0xffff0000, v16
	s_waitcnt vmcnt(36)
	v_lshlrev_b32_e32 v102, 16, v17
	v_and_b32_e32 v105, 0xffff0000, v17
	v_mul_f32_e32 v58, 0x3f317217, v128
	v_fma_f32 v58, v128, s3, -v58
	v_fmac_f32_e32 v58, 0x3377d1cf, v128
	v_fmac_f32_e32 v58, 0x3f317217, v128
	s_waitcnt vmcnt(32)
	v_lshlrev_b32_e32 v103, 16, v18
	v_and_b32_e32 v107, 0xffff0000, v18


	v_sub_f32_e32 v129, 1.0, v104
	v_max_f32_e32 v129, 0x3a800000, v129
	s_waitcnt vmcnt(30)
	v_lshlrev_b32_e32 v106, 16, v19
	v_and_b32_e32 v109, 0xffff0000, v19
	v_log_f32_e32 v129, v129
	s_waitcnt vmcnt(26)
	v_lshlrev_b32_e32 v108, 16, v20
	v_and_b32_e32 v112, 0xffff0000, v20
	s_waitcnt vmcnt(24)
	v_lshlrev_b32_e32 v110, 16, v21
	v_mul_f32_e32 v59, 0x3f317217, v129
	v_fma_f32 v59, v129, s3, -v59
	v_fmac_f32_e32 v59, 0x3377d1cf, v129
	v_fmac_f32_e32 v59, 0x3f317217, v129
	v_and_b32_e32 v114, 0xffff0000, v21
	s_waitcnt vmcnt(19)
	v_lshlrev_b32_e32 v113, 16, v22


	v_pk_add_f32 v[62:63], v[58:59], 0 op_sel_hi:[1,0]
	v_sub_f32_e32 v130, 1.0, v102
	v_max_f32_e32 v130, 0x3a800000, v130
	v_and_b32_e32 v116, 0xffff0000, v22
	s_waitcnt vmcnt(18)
	v_lshlrev_b32_e32 v115, 16, v23
	v_log_f32_e32 v130, v130
	v_and_b32_e32 v117, 0xffff0000, v23
	v_mov_b32_e32 v99, v83
	v_mov_b32_e32 v0, v82
	v_mul_f32_e32 v58, 0x3f317217, v130
	v_fma_f32 v58, v130, s3, -v58
	v_fmac_f32_e32 v58, 0x3377d1cf, v130
	v_fmac_f32_e32 v58, 0x3f317217, v130
	v_mov_b32_e32 v100, v98


	v_sub_f32_e32 v131, 1.0, v105
	v_max_f32_e32 v131, 0x3a800000, v131

	v_log_f32_e32 v131, v131
	s_nop 0
	v_mul_f32_e32 v59, 0x3f317217, v131
	v_fma_f32 v59, v131, s3, -v59
	v_fmac_f32_e32 v59, 0x3377d1cf, v131
	v_fmac_f32_e32 v59, 0x3f317217, v131


	v_sub_f32_e32 v132, 1.0, v103
	v_max_f32_e32 v132, 0x3a800000, v132
	v_pk_add_f32 v[58:59], v[58:59], v[62:63]

	v_log_f32_e32 v132, v132
	s_nop 0
	v_mul_f32_e32 v60, 0x3f317217, v132
	v_fma_f32 v60, v132, s3, -v60
	v_fmac_f32_e32 v60, 0x3377d1cf, v132
	v_fmac_f32_e32 v60, 0x3f317217, v132


	v_sub_f32_e32 v133, 1.0, v107
	v_max_f32_e32 v133, 0x3a800000, v133

	v_log_f32_e32 v133, v133
	s_nop 0
	v_mul_f32_e32 v61, 0x3f317217, v133
	v_fma_f32 v61, v133, s3, -v61
	v_fmac_f32_e32 v61, 0x3377d1cf, v133
	v_fmac_f32_e32 v61, 0x3f317217, v133
	s_nop 1


	v_sub_f32_e32 v134, 1.0, v106
	v_max_f32_e32 v134, 0x3a800000, v134
	v_pk_add_f32 v[60:61], v[60:61], v[58:59]

	v_log_f32_e32 v134, v134
	s_nop 0
	v_mul_f32_e32 v64, 0x3f317217, v134
	v_fma_f32 v64, v134, s3, -v64
	v_fmac_f32_e32 v64, 0x3377d1cf, v134
	v_fmac_f32_e32 v64, 0x3f317217, v134
	s_nop 1


	v_sub_f32_e32 v135, 1.0, v109
	v_max_f32_e32 v135, 0x3a800000, v135

	v_log_f32_e32 v135, v135
	s_nop 0
	v_mul_f32_e32 v65, 0x3f317217, v135
	v_fma_f32 v65, v135, s3, -v65
	v_fmac_f32_e32 v65, 0x3377d1cf, v135
	v_fmac_f32_e32 v65, 0x3f317217, v135
	s_nop 1


	v_pk_add_f32 v[66:67], v[64:65], v[60:61]
	v_sub_f32_e32 v136, 1.0, v108
	v_max_f32_e32 v136, 0x3a800000, v136

	v_log_f32_e32 v136, v136
	s_nop 0
	v_mul_f32_e32 v64, 0x3f317217, v136
	v_fma_f32 v64, v136, s3, -v64
	v_fmac_f32_e32 v64, 0x3377d1cf, v136
	v_fmac_f32_e32 v64, 0x3f317217, v136
	s_nop 1


	v_sub_f32_e32 v137, 1.0, v112
	v_max_f32_e32 v137, 0x3a800000, v137

	v_log_f32_e32 v137, v137
	s_nop 0
	v_mul_f32_e32 v65, 0x3f317217, v137
	v_fma_f32 v65, v137, s3, -v65
	v_fmac_f32_e32 v65, 0x3377d1cf, v137
	v_fmac_f32_e32 v65, 0x3f317217, v137
	s_nop 1


	v_pk_add_f32 v[68:69], v[64:65], v[66:67]
	v_sub_f32_e32 v138, 1.0, v110
	v_max_f32_e32 v138, 0x3a800000, v138

	v_log_f32_e32 v138, v138
	s_nop 0
	v_mul_f32_e32 v64, 0x3f317217, v138
	v_fma_f32 v64, v138, s3, -v64
	v_fmac_f32_e32 v64, 0x3377d1cf, v138
	v_fmac_f32_e32 v64, 0x3f317217, v138
	s_nop 1


	v_sub_f32_e32 v139, 1.0, v114
	v_max_f32_e32 v139, 0x3a800000, v139

	v_log_f32_e32 v139, v139
	s_nop 0
	v_mul_f32_e32 v65, 0x3f317217, v139
	v_fma_f32 v65, v139, s3, -v65
	v_fmac_f32_e32 v65, 0x3377d1cf, v139
	v_fmac_f32_e32 v65, 0x3f317217, v139
	s_nop 1


	v_pk_add_f32 v[70:71], v[64:65], v[68:69]
	v_sub_f32_e32 v140, 1.0, v113
	v_max_f32_e32 v140, 0x3a800000, v140

	v_log_f32_e32 v140, v140
	s_nop 0
	v_mul_f32_e32 v64, 0x3f317217, v140
	v_fma_f32 v64, v140, s3, -v64
	v_fmac_f32_e32 v64, 0x3377d1cf, v140
	v_fmac_f32_e32 v64, 0x3f317217, v140
	s_nop 1


	v_sub_f32_e32 v141, 1.0, v116
	v_max_f32_e32 v141, 0x3a800000, v141

	v_log_f32_e32 v141, v141
	s_nop 0
	v_mul_f32_e32 v65, 0x3f317217, v141
	v_fma_f32 v65, v141, s3, -v65
	v_fmac_f32_e32 v65, 0x3377d1cf, v141
	v_fmac_f32_e32 v65, 0x3f317217, v141
	s_nop 1


	v_pk_add_f32 v[72:73], v[64:65], v[70:71]
	v_sub_f32_e32 v142, 1.0, v115
	v_max_f32_e32 v142, 0x3a800000, v142

	v_log_f32_e32 v142, v142
	s_nop 0
	v_mul_f32_e32 v64, 0x3f317217, v142
	v_fma_f32 v64, v142, s3, -v64
	v_fmac_f32_e32 v64, 0x3377d1cf, v142
	v_fmac_f32_e32 v64, 0x3f317217, v142
	s_nop 1


	v_sub_f32_e32 v143, 1.0, v117
	v_max_f32_e32 v143, 0x3a800000, v143

	v_log_f32_e32 v143, v143
	s_nop 0
	v_mul_f32_e32 v65, 0x3f317217, v143
	v_fma_f32 v65, v143, s3, -v65
	v_fmac_f32_e32 v65, 0x3377d1cf, v143
	v_fmac_f32_e32 v65, 0x3f317217, v143
	s_nop 1


	v_pk_add_f32 v[74:75], v[64:65], v[72:73]
	v_lshlrev_b32_e32 v64, 2, v0
	v_add_u32_e32 v65, s76, v64
	ds_write_b64 v65, v[74:75]
	s_waitcnt lgkmcnt(0)
	s_barrier
	v_add_u32_e32 v111, 0, v64
	ds_read2st64_b64 v[76:79], v111 offset1:1
	ds_read2st64_b64 v[128:131], v111 offset0:2 offset1:3
	ds_read2st64_b64 v[132:135], v111 offset0:4 offset1:5
	ds_read2st64_b64 v[136:139], v111 offset0:6 offset1:7
	s_andn2_b64 vcc, exec, s[58:59]
	s_waitcnt lgkmcnt(3)
	v_pk_add_f32 v[64:65], v[76:77], 0 op_sel_hi:[1,0]
	s_nop 0
	v_pk_add_f32 v[80:81], v[64:65], v[78:79]
	v_cndmask_b32_e64 v86, 0, v65, s[10:11]
	v_cndmask_b32_e64 v87, 0, v64, s[10:11]
	s_waitcnt lgkmcnt(2)
	v_pk_add_f32 v[64:65], v[80:81], v[128:129]
	v_cndmask_b32_e64 v76, v87, v80, s[12:13]
	v_cndmask_b32_e64 v77, v86, v81, s[12:13]
	v_cndmask_b32_e64 v86, v77, v65, s[14:15]
	v_cndmask_b32_e64 v87, v76, v64, s[14:15]
	v_pk_add_f32 v[94:95], v[64:65], v[130:131]
	s_waitcnt lgkmcnt(1)
	v_pk_add_f32 v[64:65], v[94:95], v[132:133]
	v_cndmask_b32_e64 v76, v87, v94, s[16:17]
	v_cndmask_b32_e64 v77, v86, v95, s[16:17]
	v_cndmask_b32_e64 v77, v77, v65, s[18:19]
	v_cndmask_b32_e64 v76, v76, v64, s[18:19]
	v_pk_add_f32 v[96:97], v[64:65], v[134:135]
	s_nop 0
	v_cndmask_b32_e64 v88, v76, v96, s[20:21]
	v_cndmask_b32_e64 v89, v77, v97, s[20:21]
	s_waitcnt lgkmcnt(0)
	v_pk_add_f32 v[86:87], v[96:97], v[136:137]
	s_nop 0
	v_pk_add_f32 v[64:65], v[86:87], v[138:139]
	v_cndmask_b32_e64 v76, 0, v81, s[8:9]
	v_cndmask_b32_e64 v77, 0, v80, s[8:9]
	v_cndmask_b32_e64 v78, v81, v95, s[8:9]
	v_cndmask_b32_e64 v79, v80, v94, s[8:9]
	v_cndmask_b32_e64 v77, v77, v94, s[6:7]
	v_cndmask_b32_e64 v76, v76, v95, s[6:7]
	v_cndmask_b32_e64 v79, v79, v96, s[6:7]
	v_cndmask_b32_e64 v78, v78, v97, s[6:7]
	v_cndmask_b32_e64 v91, v76, v97, s[24:25]
	v_cndmask_b32_e64 v90, v77, v96, s[24:25]
	v_cndmask_b32_e64 v77, v78, v65, s[24:25]
	v_cndmask_b32_e64 v76, v79, v64, s[24:25]
	v_pk_add_f32 v[78:79], v[80:81], v[76:77] neg_lo:[0,1] neg_hi:[0,1]
	v_mul_f32_e32 v92, 0x3fb8aa3b, v90
	v_min_f32_e32 v78, 0, v78
	v_mul_f32_e32 v78, 0x3fb8aa3b, v78
	v_exp_f32_e32 v118, v78
	v_min_f32_e32 v78, 0, v79
	v_mul_f32_e32 v78, 0x3fb8aa3b, v78
	v_exp_f32_e32 v119, v78
	v_cndmask_b32_e64 v79, v89, v87, s[22:23]
	v_cndmask_b32_e64 v78, v88, v86, s[22:23]
	v_pk_add_f32 v[88:89], v[78:79], v[90:91] neg_lo:[0,1] neg_hi:[0,1]
	v_mul_f32_e32 v93, 0x3fb8aa3b, v91
	v_pk_add_f32 v[62:63], v[62:63], v[88:89]
	v_pk_add_f32 v[86:87], v[76:77], v[90:91] neg_lo:[0,1] neg_hi:[0,1]
	v_mul_f32_e32 v90, 0x3fb8aa3b, v62
	v_exp_f32_e32 v78, v93
	v_exp_f32_e32 v93, v90
	v_mul_f32_e32 v90, 0x3fb8aa3b, v63
	v_exp_f32_e32 v123, v90
	v_mul_f32_e32 v79, 0x3fb8aa3b, v84
	v_rcp_f32_e32 v90, v93
	v_exp_f32_e32 v80, v92
	v_exp_f32_e32 v92, v79
	v_mul_f32_e32 v79, 0x3fb8aa3b, v85
	v_exp_f32_e32 v122, v79
	v_min_f32_e32 v121, 0x79297b5a, v90
	v_rcp_f32_e32 v90, v123
	v_pk_add_f32 v[62:63], v[86:87], v[62:63] neg_lo:[0,1] neg_hi:[0,1]
	v_lshlrev_b32_e32 v79, 1, v0
	v_mul_f32_e32 v62, 0x3fb8aa3b, v62
	v_sub_u32_e32 v120, v111, v79
	v_lshlrev_b32_e32 v81, 16, v8
	v_and_b32_e32 v79, 0xffff0000, v8
	v_exp_f32_e32 v125, v62
	v_mul_f32_e32 v62, 0x3fb8aa3b, v63
	v_min_f32_e32 v124, 0x79297b5a, v90
	v_exp_f32_e32 v126, v62
	v_pk_mul_f32 v[90:91], v[92:93], v[80:81]
	v_pk_mul_f32 v[92:93], v[122:123], v[78:79]
	v_lshl_add_u32 v63, s39, 1, v120
	v_cvt_pk_bf16_f32 v62, v91, v93
	ds_write_b32 v63, v62 offset:8192
	v_mul_f32_e32 v62, v80, v91
	v_mul_f32_e32 v79, v78, v93
	v_cvt_pk_bf16_f32 v62, v62, v79
	ds_write_b32 v63, v62 offset:25600
	v_mul_f32_e32 v62, v90, v91
	v_mul_f32_e32 v63, v92, v93
	v_cvt_pk_bf16_f32 v79, v62, v63
	v_lshl_add_u64 v[62:63], v[0:1], 1, s[34:35]
	v_lshl_add_u64 v[122:123], s[52:53], 0, v[62:63]
	v_mul_f32_e32 v91, v121, v101
	v_mul_f32_e32 v93, v124, v104
	global_store_dword v[122:123], v79, off
	v_cvt_pk_bf16_f32 v91, v91, v93
	v_add_u32_e32 v93, s38, v120
	ds_write_b32 v93, v91 offset:43008
	v_cndmask_b32_e64 v91, 0, 1, s[58:59]
	v_mul_f32_e32 v79, v125, v101
	v_mul_f32_e32 v81, v126, v104
	v_cmp_ne_u32_e64 s[26:27], 1, v91
	v_add_u32_e32 v101, s33, v120
	s_cbranch_vccnz .LBB0_1412
	v_mul_f32_e32 v91, v119, v81
	v_mul_f32_e32 v93, v118, v79
	v_cvt_pk_bf16_f32 v91, v93, v91
	ds_write_b32 v101, v91 offset:47360
